# GEMM1 late-start delay for workgroups 128..255 set to 320 x64 clocks
# baseline (speedup 1.0000x reference)
.LBB0_106:
	v_writelane_b32 v246, s52, 32
	s_nop 1
	v_writelane_b32 v246, s53, 33
	v_writelane_b32 v246, s54, 34
	v_writelane_b32 v246, s55, 35
	v_writelane_b32 v246, s56, 36
	v_writelane_b32 v246, s57, 37
	v_writelane_b32 v246, s58, 38
	v_writelane_b32 v246, s59, 39
	v_writelane_b32 v246, s60, 40
	v_writelane_b32 v246, s61, 41
	v_writelane_b32 v246, s62, 42
	v_writelane_b32 v246, s63, 43
	v_writelane_b32 v246, s64, 44
	v_writelane_b32 v246, s65, 45
	v_writelane_b32 v246, s66, 46
	v_writelane_b32 v246, s67, 47
	s_or_b64 exec, exec, s[18:19]
	s_bitcmp0_b32 s2, 7
	s_cbranch_scc1 .Lg1d_skip
	s_sleep 127
	s_sleep 127
	s_sleep 66
